# grid-barrier release flattened: non-leader workgroups poll the top-level generation word directly instead of waiting for their XCD leader to re-publish it (arrival stays two-level)
# baseline (speedup 1.0000x reference)
.LBB0_385:
	v_readlane_b32 s0, v254, 33
	s_lshl_b32 s0, s0, 8
	s_add_u32 s0, s96, s0
	s_addc_u32 s1, s97, 0
	v_mov_b32_e32 v1, 0x1000
	v_mov_b32_e32 v3, 1
	global_atomic_add v3, v1, v3, s[0:1] offset:1024 sc0
	v_cvt_f32_u32_e32 v1, v2
	v_sub_u32_e32 v4, 0, v2
	v_rcp_iflag_f32_e32 v1, v1
	s_nop 0
	v_mul_f32_e32 v1, 0x4f7ffffe, v1
	v_cvt_u32_f32_e32 v1, v1
	v_mul_lo_u32 v4, v4, v1
	v_mul_hi_u32 v4, v1, v4
	v_add_u32_e32 v1, v1, v4
	s_waitcnt vmcnt(0)
	v_mul_hi_u32 v1, v3, v1
	v_mul_lo_u32 v4, v1, v2
	v_sub_u32_e32 v4, v3, v4
	v_add_u32_e32 v5, 1, v1
	v_cmp_ge_u32_e32 vcc, v4, v2
	v_add_u32_e32 v3, 1, v3
	s_nop 0
	v_cndmask_b32_e32 v1, v1, v5, vcc
	v_sub_u32_e32 v5, v4, v2
	v_cndmask_b32_e32 v4, v4, v5, vcc
	v_add_u32_e32 v5, 1, v1
	v_cmp_ge_u32_e32 vcc, v4, v2
	s_nop 1
	v_cndmask_b32_e32 v1, v1, v5, vcc
	v_mul_lo_u32 v4, v2, v1
	v_add_u32_e32 v2, v4, v2
	v_cmp_ne_u32_e32 vcc, v3, v2
	s_and_saveexec_b64 s[6:7], vcc
	s_xor_b64 s[6:7], exec, s[6:7]
	s_cbranch_execz .LBB0_399
	s_waitcnt lgkmcnt(0)
	v_mov_b32_e32 v0, 0x5100
	global_load_dword v0, v0, s[56:57] offset:1024 sc1
	s_add_u32 s12, s56, 0x5500
	s_addc_u32 s13, s57, 0
	s_waitcnt vmcnt(0)
	v_cmp_eq_u32_e32 vcc, v0, v1
	s_and_saveexec_b64 s[8:9], vcc
	s_cbranch_execz .LBB0_398
	s_add_u32 s10, s56, 0x2200
	s_addc_u32 s11, s57, 0
	s_mov_b32 s26, 1
	s_mov_b64 s[14:15], 0
	v_mov_b32_e32 v0, 0
	s_branch .LBB0_389

.LBB0_480:
	v_readlane_b32 s6, v254, 33
	s_lshl_b32 s6, s6, 8
	s_add_u32 s6, s96, s6
	s_addc_u32 s7, s97, 0
	v_mov_b32_e32 v1, 0x1000
	v_mov_b32_e32 v3, 1
	global_atomic_add v3, v1, v3, s[6:7] offset:1024 sc0
	v_cvt_f32_u32_e32 v1, v2
	v_sub_u32_e32 v4, 0, v2
	v_rcp_iflag_f32_e32 v1, v1
	s_nop 0
	v_mul_f32_e32 v1, 0x4f7ffffe, v1
	v_cvt_u32_f32_e32 v1, v1
	v_mul_lo_u32 v4, v4, v1
	v_mul_hi_u32 v4, v1, v4
	v_add_u32_e32 v1, v1, v4
	s_waitcnt vmcnt(0)
	v_mul_hi_u32 v1, v3, v1
	v_mul_lo_u32 v4, v1, v2
	v_sub_u32_e32 v4, v3, v4
	v_add_u32_e32 v5, 1, v1
	v_cmp_ge_u32_e32 vcc, v4, v2
	v_add_u32_e32 v3, 1, v3
	s_nop 0
	v_cndmask_b32_e32 v1, v1, v5, vcc
	v_sub_u32_e32 v5, v4, v2
	v_cndmask_b32_e32 v4, v4, v5, vcc
	v_add_u32_e32 v5, 1, v1
	v_cmp_ge_u32_e32 vcc, v4, v2
	s_nop 1
	v_cndmask_b32_e32 v1, v1, v5, vcc
	v_mul_lo_u32 v4, v2, v1
	v_add_u32_e32 v2, v4, v2
	v_cmp_ne_u32_e32 vcc, v3, v2
	s_and_saveexec_b64 s[10:11], vcc
	s_xor_b64 s[10:11], exec, s[10:11]
	s_cbranch_execz .LBB0_494
	s_waitcnt lgkmcnt(0)
	v_mov_b32_e32 v0, 0x5100
	global_load_dword v0, v0, s[56:57] offset:1024 sc1
	s_add_u32 s20, s56, 0x5500
	s_addc_u32 s21, s57, 0
	s_waitcnt vmcnt(0)
	v_cmp_eq_u32_e32 vcc, v0, v1
	s_and_saveexec_b64 s[14:15], vcc
	s_cbranch_execz .LBB0_493
	s_add_u32 s18, s56, 0x2200
	s_addc_u32 s19, s57, 0
	s_mov_b32 s30, 1
	s_mov_b64 s[22:23], 0
	v_mov_b32_e32 v0, 0
	s_branch .LBB0_484

.LBB0_632:
	v_readlane_b32 s3, v254, 33
	s_lshl_b32 s3, s3, 8
	s_add_u32 s6, s96, s3
	s_addc_u32 s7, s97, 0
	v_mov_b32_e32 v1, 0x1000
	v_mov_b32_e32 v3, 1
	global_atomic_add v3, v1, v3, s[6:7] offset:1024 sc0
	v_cvt_f32_u32_e32 v1, v2
	v_sub_u32_e32 v4, 0, v2
	v_rcp_iflag_f32_e32 v1, v1
	s_nop 0
	v_mul_f32_e32 v1, 0x4f7ffffe, v1
	v_cvt_u32_f32_e32 v1, v1
	v_mul_lo_u32 v4, v4, v1
	v_mul_hi_u32 v4, v1, v4
	v_add_u32_e32 v1, v1, v4
	s_waitcnt vmcnt(0)
	v_mul_hi_u32 v1, v3, v1
	v_mul_lo_u32 v4, v1, v2
	v_sub_u32_e32 v4, v3, v4
	v_add_u32_e32 v5, 1, v1
	v_cmp_ge_u32_e32 vcc, v4, v2
	v_add_u32_e32 v3, 1, v3
	s_nop 0
	v_cndmask_b32_e32 v1, v1, v5, vcc
	v_sub_u32_e32 v5, v4, v2
	v_cndmask_b32_e32 v4, v4, v5, vcc
	v_add_u32_e32 v5, 1, v1
	v_cmp_ge_u32_e32 vcc, v4, v2
	s_nop 1
	v_cndmask_b32_e32 v1, v1, v5, vcc
	v_mul_lo_u32 v4, v2, v1
	v_add_u32_e32 v2, v4, v2
	v_cmp_ne_u32_e32 vcc, v3, v2
	s_and_saveexec_b64 s[8:9], vcc
	s_xor_b64 s[8:9], exec, s[8:9]
	s_cbranch_execz .LBB0_646
	s_waitcnt lgkmcnt(0)
	v_mov_b32_e32 v0, 0x5100
	global_load_dword v0, v0, s[56:57] offset:1024 sc1
	s_add_u32 s18, s56, 0x5500
	s_addc_u32 s19, s57, 0
	s_waitcnt vmcnt(0)
	v_cmp_eq_u32_e32 vcc, v0, v1
	s_and_saveexec_b64 s[12:13], vcc
	s_cbranch_execz .LBB0_645
	s_add_u32 s14, s56, 0x2200
	s_addc_u32 s15, s57, 0
	s_mov_b32 s3, 1
	s_mov_b64 s[20:21], 0
	v_mov_b32_e32 v0, 0
	s_branch .LBB0_636

.LBB0_1105:
	v_readlane_b32 s6, v254, 33
	s_lshl_b32 s6, s6, 8
	s_add_u32 s6, s96, s6
	s_addc_u32 s7, s97, 0
	v_mov_b32_e32 v1, 0x1000
	v_mov_b32_e32 v3, 1
	global_atomic_add v3, v1, v3, s[6:7] offset:1024 sc0
	v_cvt_f32_u32_e32 v1, v2
	v_sub_u32_e32 v4, 0, v2
	v_rcp_iflag_f32_e32 v1, v1
	s_nop 0
	v_mul_f32_e32 v1, 0x4f7ffffe, v1
	v_cvt_u32_f32_e32 v1, v1
	v_mul_lo_u32 v4, v4, v1
	v_mul_hi_u32 v4, v1, v4
	v_add_u32_e32 v1, v1, v4
	s_waitcnt vmcnt(0)
	v_mul_hi_u32 v1, v3, v1
	v_mul_lo_u32 v4, v1, v2
	v_sub_u32_e32 v4, v3, v4
	v_add_u32_e32 v5, 1, v1
	v_cmp_ge_u32_e32 vcc, v4, v2
	v_add_u32_e32 v3, 1, v3
	s_nop 0
	v_cndmask_b32_e32 v1, v1, v5, vcc
	v_sub_u32_e32 v5, v4, v2
	v_cndmask_b32_e32 v4, v4, v5, vcc
	v_add_u32_e32 v5, 1, v1
	v_cmp_ge_u32_e32 vcc, v4, v2
	s_nop 1
	v_cndmask_b32_e32 v1, v1, v5, vcc
	v_mul_lo_u32 v4, v2, v1
	v_add_u32_e32 v2, v4, v2
	v_cmp_ne_u32_e32 vcc, v3, v2
	s_and_saveexec_b64 s[8:9], vcc
	s_xor_b64 s[8:9], exec, s[8:9]
	s_cbranch_execz .LBB0_1119
	s_waitcnt lgkmcnt(0)
	v_mov_b32_e32 v0, 0x5100
	global_load_dword v0, v0, s[56:57] offset:1024 sc1
	s_add_u32 s18, s56, 0x5500
	s_addc_u32 s19, s57, 0
	s_waitcnt vmcnt(0)
	v_cmp_eq_u32_e32 vcc, v0, v1
	s_and_saveexec_b64 s[12:13], vcc
	s_cbranch_execz .LBB0_1118
	s_add_u32 s14, s56, 0x2200
	s_addc_u32 s15, s57, 0
	s_mov_b32 s30, 1
	s_mov_b64 s[20:21], 0
	v_mov_b32_e32 v0, 0
	s_branch .LBB0_1109

.LBB0_1366:
	v_readlane_b32 s4, v254, 33
	s_lshl_b32 s4, s4, 8
	s_add_u32 s4, s96, s4
	s_addc_u32 s5, s97, 0
	v_mov_b32_e32 v1, 0x1000
	v_mov_b32_e32 v3, 1
	global_atomic_add v3, v1, v3, s[4:5] offset:1024 sc0
	v_cvt_f32_u32_e32 v1, v2
	v_sub_u32_e32 v4, 0, v2
	v_rcp_iflag_f32_e32 v1, v1
	s_nop 0
	v_mul_f32_e32 v1, 0x4f7ffffe, v1
	v_cvt_u32_f32_e32 v1, v1
	v_mul_lo_u32 v4, v4, v1
	v_mul_hi_u32 v4, v1, v4
	v_add_u32_e32 v1, v1, v4
	s_waitcnt vmcnt(0)
	v_mul_hi_u32 v1, v3, v1
	v_mul_lo_u32 v4, v1, v2
	v_sub_u32_e32 v4, v3, v4
	v_add_u32_e32 v5, 1, v1
	v_cmp_ge_u32_e32 vcc, v4, v2
	v_add_u32_e32 v3, 1, v3
	s_nop 0
	v_cndmask_b32_e32 v1, v1, v5, vcc
	v_sub_u32_e32 v5, v4, v2
	v_cndmask_b32_e32 v4, v4, v5, vcc
	v_add_u32_e32 v5, 1, v1
	v_cmp_ge_u32_e32 vcc, v4, v2
	s_nop 1
	v_cndmask_b32_e32 v1, v1, v5, vcc
	v_mul_lo_u32 v4, v2, v1
	v_add_u32_e32 v2, v4, v2
	v_cmp_ne_u32_e32 vcc, v3, v2
	s_and_saveexec_b64 s[6:7], vcc
	s_xor_b64 s[6:7], exec, s[6:7]
	s_cbranch_execz .LBB0_1380
	s_waitcnt lgkmcnt(0)
	v_mov_b32_e32 v0, 0x5100
	global_load_dword v0, v0, s[56:57] offset:1024 sc1
	s_add_u32 s12, s56, 0x5500
	s_addc_u32 s13, s57, 0
	s_waitcnt vmcnt(0)
	v_cmp_eq_u32_e32 vcc, v0, v1
	s_and_saveexec_b64 s[8:9], vcc
	s_cbranch_execz .LBB0_1379
	s_add_u32 s10, s56, 0x2200
	s_addc_u32 s11, s57, 0
	s_mov_b32 s24, 1
	s_mov_b64 s[14:15], 0
	v_mov_b32_e32 v0, 0
	s_branch .LBB0_1370
